# final output stores write-through (sc1), as the other wide streaming stores
# speedup vs baseline: 1.0036x; 1.0036x over previous
.Lfz_bar_end_a:
	s_or_b64 exec, exec, s[0:1]
	s_barrier
	v_lshrrev_b32_e32 v232, 12, v228
	v_lshlrev_b32_e32 v232, 4, v232
	v_add_u32_e32 v233, 0x0, v232
	v_add_u32_e32 v234, 0x100, v232
	v_add_u32_e32 v235, 0x200, v232
	v_add_u32_e32 v236, 0x300, v232
	v_add_u32_e32 v237, 0x800, v232
	v_add_u32_e32 v238, 0x900, v232
	v_add_u32_e32 v239, 0xa00, v232
	v_add_u32_e32 v240, 0xb00, v232
	global_load_dwordx4 v[180:183], v233, s[50:51]
	global_load_dwordx4 v[184:187], v234, s[50:51]
	global_load_dwordx4 v[188:191], v235, s[50:51]
	global_load_dwordx4 v[192:195], v236, s[50:51]
	global_load_dwordx4 v[196:199], v237, s[50:51]
	global_load_dwordx4 v[200:203], v238, s[50:51]
	global_load_dwordx4 v[204:207], v239, s[50:51]
	global_load_dwordx4 v[208:211], v240, s[50:51]
	s_waitcnt vmcnt(0)
	v_mov_b32_e32 v242, 0x3a800000
	v_mov_b32_e32 v243, 0x358637bd
	v_add_f32_e32 v160, v180, v181
	v_add_f32_e32 v160, v160, v182
	v_add_f32_e32 v160, v160, v183
	v_fma_f32 v160, v160, v242, v243
	v_add_f32_e32 v161, v184, v185
	v_add_f32_e32 v161, v161, v186
	v_add_f32_e32 v161, v161, v187
	v_fma_f32 v161, v161, v242, v243
	v_add_f32_e32 v162, v188, v189
	v_add_f32_e32 v162, v162, v190
	v_add_f32_e32 v162, v162, v191
	v_fma_f32 v162, v162, v242, v243
	v_add_f32_e32 v163, v192, v193
	v_add_f32_e32 v163, v163, v194
	v_add_f32_e32 v163, v163, v195
	v_fma_f32 v163, v163, v242, v243
	v_add_f32_e32 v164, v196, v197
	v_add_f32_e32 v164, v164, v198
	v_add_f32_e32 v164, v164, v199
	v_fma_f32 v164, v164, v242, v243
	v_add_f32_e32 v165, v200, v201
	v_add_f32_e32 v165, v165, v202
	v_add_f32_e32 v165, v165, v203
	v_fma_f32 v165, v165, v242, v243
	v_add_f32_e32 v166, v204, v205
	v_add_f32_e32 v166, v166, v206
	v_add_f32_e32 v166, v166, v207
	v_fma_f32 v166, v166, v242, v243
	v_add_f32_e32 v167, v208, v209
	v_add_f32_e32 v167, v167, v210
	v_add_f32_e32 v167, v167, v211
	v_fma_f32 v167, v167, v242, v243
	v_rsq_f32_e32 v160, v160
	v_rsq_f32_e32 v161, v161
	v_rsq_f32_e32 v162, v162
	v_rsq_f32_e32 v163, v163
	v_rsq_f32_e32 v164, v164
	v_rsq_f32_e32 v165, v165
	v_rsq_f32_e32 v166, v166
	v_rsq_f32_e32 v167, v167
	s_nop 0
	s_add_u32 s48, s42, 0x0
	s_addc_u32 s49, s43, 0
	v_mul_f32_e32 v140, v140, v160
	v_mul_f32_e32 v141, v141, v160
	v_mul_f32_e32 v142, v142, v160
	v_mul_f32_e32 v143, v143, v160
	v_pk_mul_f32 v[140:141], v[140:141], v[212:213]
	v_pk_mul_f32 v[142:143], v[142:143], v[214:215]
	v_mul_f32_e32 v136, v136, v160
	v_mul_f32_e32 v137, v137, v160
	v_mul_f32_e32 v138, v138, v160
	v_mul_f32_e32 v139, v139, v160
	v_pk_mul_f32 v[136:137], v[136:137], v[216:217]
	v_pk_mul_f32 v[138:139], v[138:139], v[218:219]
	v_mul_f32_e32 v132, v132, v160
	v_mul_f32_e32 v133, v133, v160
	v_mul_f32_e32 v134, v134, v160
	v_mul_f32_e32 v135, v135, v160
	v_pk_mul_f32 v[132:133], v[132:133], v[220:221]
	v_pk_mul_f32 v[134:135], v[134:135], v[222:223]
	v_mul_f32_e32 v128, v128, v160
	v_mul_f32_e32 v129, v129, v160
	v_mul_f32_e32 v130, v130, v160
	v_mul_f32_e32 v131, v131, v160
	v_pk_mul_f32 v[128:129], v[128:129], v[224:225]
	v_pk_mul_f32 v[130:131], v[130:131], v[226:227]
	global_store_dwordx4 v228, v[140:143], s[48:49] sc1
	global_store_dwordx4 v228, v[136:139], s[48:49] offset:64 sc1
	global_store_dwordx4 v228, v[132:135], s[48:49] offset:512 sc1
	global_store_dwordx4 v228, v[128:131], s[48:49] offset:576 sc1
	s_add_u32 s48, s42, 0x10000
	s_addc_u32 s49, s43, 0
	v_mul_f32_e32 v124, v124, v161
	v_mul_f32_e32 v125, v125, v161
	v_mul_f32_e32 v126, v126, v161
	v_mul_f32_e32 v127, v127, v161
	v_pk_mul_f32 v[124:125], v[124:125], v[212:213]
	v_pk_mul_f32 v[126:127], v[126:127], v[214:215]
	v_mul_f32_e32 v120, v120, v161
	v_mul_f32_e32 v121, v121, v161
	v_mul_f32_e32 v122, v122, v161
	v_mul_f32_e32 v123, v123, v161
	v_pk_mul_f32 v[120:121], v[120:121], v[216:217]
	v_pk_mul_f32 v[122:123], v[122:123], v[218:219]
	v_mul_f32_e32 v116, v116, v161
	v_mul_f32_e32 v117, v117, v161
	v_mul_f32_e32 v118, v118, v161
	v_mul_f32_e32 v119, v119, v161
	v_pk_mul_f32 v[116:117], v[116:117], v[220:221]
	v_pk_mul_f32 v[118:119], v[118:119], v[222:223]
	v_mul_f32_e32 v112, v112, v161
	v_mul_f32_e32 v113, v113, v161
	v_mul_f32_e32 v114, v114, v161
	v_mul_f32_e32 v115, v115, v161
	v_pk_mul_f32 v[112:113], v[112:113], v[224:225]
	v_pk_mul_f32 v[114:115], v[114:115], v[226:227]
	global_store_dwordx4 v228, v[124:127], s[48:49] sc1
	global_store_dwordx4 v228, v[120:123], s[48:49] offset:64 sc1
	global_store_dwordx4 v228, v[116:119], s[48:49] offset:512 sc1
	global_store_dwordx4 v228, v[112:115], s[48:49] offset:576 sc1
	s_add_u32 s48, s42, 0x20000
	s_addc_u32 s49, s43, 0
	v_mul_f32_e32 v108, v108, v162
	v_mul_f32_e32 v109, v109, v162
	v_mul_f32_e32 v110, v110, v162
	v_mul_f32_e32 v111, v111, v162
	v_pk_mul_f32 v[108:109], v[108:109], v[212:213]
	v_pk_mul_f32 v[110:111], v[110:111], v[214:215]
	v_mul_f32_e32 v104, v104, v162
	v_mul_f32_e32 v105, v105, v162
	v_mul_f32_e32 v106, v106, v162
	v_mul_f32_e32 v107, v107, v162
	v_pk_mul_f32 v[104:105], v[104:105], v[216:217]
	v_pk_mul_f32 v[106:107], v[106:107], v[218:219]
	v_mul_f32_e32 v96, v96, v162
	v_mul_f32_e32 v97, v97, v162
	v_mul_f32_e32 v98, v98, v162
	v_mul_f32_e32 v99, v99, v162
	v_pk_mul_f32 v[96:97], v[96:97], v[220:221]
	v_pk_mul_f32 v[98:99], v[98:99], v[222:223]
	v_mul_f32_e32 v88, v88, v162
	v_mul_f32_e32 v89, v89, v162
	v_mul_f32_e32 v90, v90, v162
	v_mul_f32_e32 v91, v91, v162
	v_pk_mul_f32 v[88:89], v[88:89], v[224:225]
	v_pk_mul_f32 v[90:91], v[90:91], v[226:227]
	global_store_dwordx4 v228, v[108:111], s[48:49] sc1
	global_store_dwordx4 v228, v[104:107], s[48:49] offset:64 sc1
	global_store_dwordx4 v228, v[96:99], s[48:49] offset:512 sc1
	global_store_dwordx4 v228, v[88:91], s[48:49] offset:576 sc1
	s_add_u32 s48, s42, 0x30000
	s_addc_u32 s49, s43, 0
	v_mul_f32_e32 v76, v76, v163
	v_mul_f32_e32 v77, v77, v163
	v_mul_f32_e32 v78, v78, v163
	v_mul_f32_e32 v79, v79, v163
	v_pk_mul_f32 v[76:77], v[76:77], v[212:213]
	v_pk_mul_f32 v[78:79], v[78:79], v[214:215]
	v_mul_f32_e32 v72, v72, v163
	v_mul_f32_e32 v73, v73, v163
	v_mul_f32_e32 v74, v74, v163
	v_mul_f32_e32 v75, v75, v163
	v_pk_mul_f32 v[72:73], v[72:73], v[216:217]
	v_pk_mul_f32 v[74:75], v[74:75], v[218:219]
	v_mul_f32_e32 v68, v68, v163
	v_mul_f32_e32 v69, v69, v163
	v_mul_f32_e32 v70, v70, v163
	v_mul_f32_e32 v71, v71, v163
	v_pk_mul_f32 v[68:69], v[68:69], v[220:221]
	v_pk_mul_f32 v[70:71], v[70:71], v[222:223]
	v_mul_f32_e32 v64, v64, v163
	v_mul_f32_e32 v65, v65, v163
	v_mul_f32_e32 v66, v66, v163
	v_mul_f32_e32 v67, v67, v163
	v_pk_mul_f32 v[64:65], v[64:65], v[224:225]
	v_pk_mul_f32 v[66:67], v[66:67], v[226:227]
	global_store_dwordx4 v228, v[76:79], s[48:49] sc1
	global_store_dwordx4 v228, v[72:75], s[48:49] offset:64 sc1
	global_store_dwordx4 v228, v[68:71], s[48:49] offset:512 sc1
	global_store_dwordx4 v228, v[64:67], s[48:49] offset:576 sc1
	s_add_u32 s48, s42, 0x80000
	s_addc_u32 s49, s43, 0
	v_mul_f32_e32 v60, v60, v164
	v_mul_f32_e32 v61, v61, v164
	v_mul_f32_e32 v62, v62, v164
	v_mul_f32_e32 v63, v63, v164
	v_pk_mul_f32 v[60:61], v[60:61], v[212:213]
	v_pk_mul_f32 v[62:63], v[62:63], v[214:215]
	v_mul_f32_e32 v56, v56, v164
	v_mul_f32_e32 v57, v57, v164
	v_mul_f32_e32 v58, v58, v164
	v_mul_f32_e32 v59, v59, v164
	v_pk_mul_f32 v[56:57], v[56:57], v[216:217]
	v_pk_mul_f32 v[58:59], v[58:59], v[218:219]
	v_mul_f32_e32 v52, v52, v164
	v_mul_f32_e32 v53, v53, v164
	v_mul_f32_e32 v54, v54, v164
	v_mul_f32_e32 v55, v55, v164
	v_pk_mul_f32 v[52:53], v[52:53], v[220:221]
	v_pk_mul_f32 v[54:55], v[54:55], v[222:223]
	v_mul_f32_e32 v48, v48, v164
	v_mul_f32_e32 v49, v49, v164
	v_mul_f32_e32 v50, v50, v164
	v_mul_f32_e32 v51, v51, v164
	v_pk_mul_f32 v[48:49], v[48:49], v[224:225]
	v_pk_mul_f32 v[50:51], v[50:51], v[226:227]
	global_store_dwordx4 v228, v[60:63], s[48:49] sc1
	global_store_dwordx4 v228, v[56:59], s[48:49] offset:64 sc1
	global_store_dwordx4 v228, v[52:55], s[48:49] offset:512 sc1
	global_store_dwordx4 v228, v[48:51], s[48:49] offset:576 sc1
	s_add_u32 s48, s42, 0x90000
	s_addc_u32 s49, s43, 0
	v_mul_f32_e32 v44, v44, v165
	v_mul_f32_e32 v45, v45, v165
	v_mul_f32_e32 v46, v46, v165
	v_mul_f32_e32 v47, v47, v165
	v_pk_mul_f32 v[44:45], v[44:45], v[212:213]
	v_pk_mul_f32 v[46:47], v[46:47], v[214:215]
	v_mul_f32_e32 v40, v40, v165
	v_mul_f32_e32 v41, v41, v165
	v_mul_f32_e32 v42, v42, v165
	v_mul_f32_e32 v43, v43, v165
	v_pk_mul_f32 v[40:41], v[40:41], v[216:217]
	v_pk_mul_f32 v[42:43], v[42:43], v[218:219]
	v_mul_f32_e32 v36, v36, v165
	v_mul_f32_e32 v37, v37, v165
	v_mul_f32_e32 v38, v38, v165
	v_mul_f32_e32 v39, v39, v165
	v_pk_mul_f32 v[36:37], v[36:37], v[220:221]
	v_pk_mul_f32 v[38:39], v[38:39], v[222:223]
	v_mul_f32_e32 v32, v32, v165
	v_mul_f32_e32 v33, v33, v165
	v_mul_f32_e32 v34, v34, v165
	v_mul_f32_e32 v35, v35, v165
	v_pk_mul_f32 v[32:33], v[32:33], v[224:225]
	v_pk_mul_f32 v[34:35], v[34:35], v[226:227]
	global_store_dwordx4 v228, v[44:47], s[48:49] sc1
	global_store_dwordx4 v228, v[40:43], s[48:49] offset:64 sc1
	global_store_dwordx4 v228, v[36:39], s[48:49] offset:512 sc1
	global_store_dwordx4 v228, v[32:35], s[48:49] offset:576 sc1
	s_add_u32 s48, s42, 0xa0000
	s_addc_u32 s49, s43, 0
	v_mul_f32_e32 v28, v28, v166
	v_mul_f32_e32 v29, v29, v166
	v_mul_f32_e32 v30, v30, v166
	v_mul_f32_e32 v31, v31, v166
	v_pk_mul_f32 v[28:29], v[28:29], v[212:213]
	v_pk_mul_f32 v[30:31], v[30:31], v[214:215]
	v_mul_f32_e32 v24, v24, v166
	v_mul_f32_e32 v25, v25, v166
	v_mul_f32_e32 v26, v26, v166
	v_mul_f32_e32 v27, v27, v166
	v_pk_mul_f32 v[24:25], v[24:25], v[216:217]
	v_pk_mul_f32 v[26:27], v[26:27], v[218:219]
	v_mul_f32_e32 v16, v16, v166
	v_mul_f32_e32 v17, v17, v166
	v_mul_f32_e32 v18, v18, v166
	v_mul_f32_e32 v19, v19, v166
	v_pk_mul_f32 v[16:17], v[16:17], v[220:221]
	v_pk_mul_f32 v[18:19], v[18:19], v[222:223]
	v_mul_f32_e32 v8, v8, v166
	v_mul_f32_e32 v9, v9, v166
	v_mul_f32_e32 v10, v10, v166
	v_mul_f32_e32 v11, v11, v166
	v_pk_mul_f32 v[8:9], v[8:9], v[224:225]
	v_pk_mul_f32 v[10:11], v[10:11], v[226:227]
	global_store_dwordx4 v228, v[28:31], s[48:49] sc1
	global_store_dwordx4 v228, v[24:27], s[48:49] offset:64 sc1
	global_store_dwordx4 v228, v[16:19], s[48:49] offset:512 sc1
	global_store_dwordx4 v228, v[8:11], s[48:49] offset:576 sc1
	s_add_u32 s48, s42, 0xb0000
	s_addc_u32 s49, s43, 0
	v_mul_f32_e32 v20, v20, v167
	v_mul_f32_e32 v21, v21, v167
	v_mul_f32_e32 v22, v22, v167
	v_mul_f32_e32 v23, v23, v167
	v_pk_mul_f32 v[20:21], v[20:21], v[212:213]
	v_pk_mul_f32 v[22:23], v[22:23], v[214:215]
	v_mul_f32_e32 v12, v12, v167
	v_mul_f32_e32 v13, v13, v167
	v_mul_f32_e32 v14, v14, v167
	v_mul_f32_e32 v15, v15, v167
	v_pk_mul_f32 v[12:13], v[12:13], v[216:217]
	v_pk_mul_f32 v[14:15], v[14:15], v[218:219]
	v_mul_f32_e32 v4, v4, v167
	v_mul_f32_e32 v5, v5, v167
	v_mul_f32_e32 v6, v6, v167
	v_mul_f32_e32 v7, v7, v167
	v_pk_mul_f32 v[4:5], v[4:5], v[220:221]
	v_pk_mul_f32 v[6:7], v[6:7], v[222:223]
	v_mul_f32_e32 v0, v0, v167
	v_mul_f32_e32 v1, v1, v167
	v_mul_f32_e32 v2, v2, v167
	v_mul_f32_e32 v3, v3, v167
	v_pk_mul_f32 v[0:1], v[0:1], v[224:225]
	v_pk_mul_f32 v[2:3], v[2:3], v[226:227]
	global_store_dwordx4 v228, v[20:23], s[48:49] sc1
	global_store_dwordx4 v228, v[12:15], s[48:49] offset:64 sc1
	global_store_dwordx4 v228, v[4:7], s[48:49] offset:512 sc1
	global_store_dwordx4 v228, v[0:3], s[48:49] offset:576 sc1
